# cmp loop overlap weights built per packed dword (one compare + select) into separate register quads for the two importance MFMAs
# speedup vs baseline: 1.0107x; 1.0107x over previous
; #define LAS __attribute__((address_space(3)))
; #define LDS_WAIT() asm volatile("s_waitcnt lgkmcnt(0)" ::: "memory")
; #define MFMA32(a, b, c) __builtin_amdgcn_mfma_f32_32x32x16_bf16((a), (b), (c), 0, 0, 0)
; template <bool CMP> DI void tile_compute(LAS unsigned char* lds, int buf, const bf16x8 (&q)[4], int lo, int hv, ASt& st, f32x16& imp0, f32x16& imp1, int jt, LAS float* wsf, int lane) {
;     ...
;     const float msub = (!anyPart && dead) ? 1e30f : mnew;
; #pragma unroll
;     for (int rg = 0; rg < 16; ++rg) { p0[rg] = __builtin_amdgcn_exp2f(p0[rg] - msub); p1[rg] = __builtin_amdgcn_exp2f(p1[rg] - msub); sum += p0[rg] + p1[rg]; }
;     st.l = st.l * alpha + sum;
;     if (__builtin_amdgcn_ballot_w64(alpha != 1.f) != 0ull) {
;         if (hi == 0) wsf[r] = alpha;
;         LDS_WAIT();
; #pragma unroll
;         for (int g4 = 0; g4 < 4; ++g4) { const f32x4 f = *(const LAS f32x4*)(wsf + 8 * g4 + 4 * hi);
; #pragma unroll
;             for (int k = 0; k < 4; ++k) { st.o0[4 * g4 + k] *= f[k]; st.o1[4 * g4 + k] *= f[k]; if (CMP) { imp0[4 * g4 + k] *= f[k]; imp1[4 * g4 + k] *= f[k]; } } }
;         LDS_WAIT();
;     }
;     bf16x8 pa[4];
;     pa[0] = pack8(p0[0], p0[1], p0[2], p0[3], p0[4], p0[5], p0[6], p0[7]); pa[1] = pack8(p0[8], p0[9], p0[10], p0[11], p0[12], p0[13], p0[14], p0[15]);
;     pa[2] = pack8(p1[0], p1[1], p1[2], p1[3], p1[4], p1[5], p1[6], p1[7]); pa[3] = pack8(p1[8], p1[9], p1[10], p1[11], p1[12], p1[13], p1[14], p1[15]);
;     const LAS unsigned char* vb = lds + A_VT + buf * 8192 + (4 * hi + ((lane & 15) >> 2)) * 64 + ((lane >> 4) & 1) * 32 + (lane & 3) * 8;
; #pragma unroll
;     for (int s = 0; s < 4; ++s) {
;         const bf16x8 v0 = cat8(vtr(vb + s * 1024), vtr(vb + s * 1024 + 512));
;         const bf16x8 v1 = cat8(vtr(vb + 4096 + s * 1024), vtr(vb + 4096 + s * 1024 + 512));
;         st.o0 = MFMA32(pa[s], v0, st.o0); st.o1 = MFMA32(pa[s], v1, st.o1);
;     }
;     if (CMP) {
; #pragma unroll
;         for (int s = 0; s < 4; ++s) {
;             bf16x8 w0, w1;
; #pragma unroll
;             for (int j = 0; j < 8; ++j) { const int jj = 64 * jt + 16 * s + 8 * (j >> 2) + 4 * hi + (j & 3);
;                 const int n0 = r, n1 = 32 + r;
;                 w0[j] = (jj >= 4 * n0 - 1 && jj <= 4 * n0 + 3) ? (short)0x3F80 : (short)0;
;                 w1[j] = (jj >= 4 * n1 - 1 && jj <= 4 * n1 + 3) ? (short)0x3F80 : (short)0; }
.LBB0_555:
	v_cndmask_b32_e64 v234, v141, v223, s[78:79]
	v_sub_f32_e32 v84, v84, v234
	v_sub_f32_e32 v68, v68, v234
	v_exp_f32_e32 v235, v84
	v_exp_f32_e32 v68, v68
	v_sub_f32_e32 v85, v85, v234
	v_sub_f32_e32 v69, v69, v234
	v_exp_f32_e32 v85, v85
	v_exp_f32_e32 v69, v69
	v_sub_f32_e32 v86, v86, v234
	v_sub_f32_e32 v70, v70, v234
	v_exp_f32_e32 v86, v86
	v_exp_f32_e32 v70, v70
	v_sub_f32_e32 v87, v87, v234
	v_sub_f32_e32 v71, v71, v234
	v_exp_f32_e32 v87, v87
	v_exp_f32_e32 v71, v71
	v_add_f32_e32 v84, v68, v235
	v_add_f32_e32 v84, 0, v84
	v_add_f32_e32 v236, v69, v85
	v_add_f32_e32 v84, v236, v84
	v_add_f32_e32 v236, v70, v86
	v_add_f32_e32 v84, v236, v84
	v_add_f32_e32 v236, v71, v87
	v_sub_f32_e32 v88, v88, v234
	v_sub_f32_e32 v72, v72, v234
	v_add_f32_e32 v84, v236, v84
	v_exp_f32_e32 v88, v88
	v_exp_f32_e32 v236, v72
	v_sub_f32_e32 v73, v73, v234
	v_exp_f32_e32 v237, v73
	v_sub_f32_e32 v74, v74, v234
	v_add_f32_e32 v72, v236, v88
	v_add_f32_e32 v72, v72, v84
	v_sub_f32_e32 v84, v89, v234
	v_exp_f32_e32 v89, v84
	v_sub_f32_e32 v75, v75, v234
	v_exp_f32_e32 v75, v75
	v_sub_f32_e32 v76, v76, v234
	v_add_f32_e32 v73, v237, v89
	v_add_f32_e32 v72, v73, v72
	v_sub_f32_e32 v73, v90, v234
	v_exp_f32_e32 v73, v73
	v_exp_f32_e32 v90, v74
	v_sub_f32_e32 v77, v77, v234
	v_sub_f32_e32 v78, v78, v234
	v_sub_f32_e32 v79, v79, v234
	v_add_f32_e32 v74, v90, v73
	v_add_f32_e32 v72, v74, v72
	v_sub_f32_e32 v74, v91, v234
	v_exp_f32_e32 v74, v74
	v_sub_f32_e32 v80, v80, v234
	v_subrev_u32_e32 v231, 64, v231
	v_add_f32_e32 v84, v75, v74
	v_add_f32_e32 v72, v84, v72
	v_sub_f32_e32 v84, v92, v234
	v_exp_f32_e32 v91, v84
	v_exp_f32_e32 v92, v76
	v_cvt_pk_bf16_f32 v75, v90, v75
	v_add_f32_e32 v76, v92, v91
	v_add_f32_e32 v72, v76, v72
	v_sub_f32_e32 v76, v93, v234
	v_exp_f32_e32 v76, v76
	v_exp_f32_e32 v93, v77
	s_nop 0
	v_add_f32_e32 v77, v93, v76
	v_add_f32_e32 v72, v77, v72
	v_sub_f32_e32 v77, v94, v234
	v_exp_f32_e32 v77, v77
	v_exp_f32_e32 v94, v78
	v_cvt_pk_bf16_f32 v76, v91, v76
	v_add_f32_e32 v78, v94, v77
	v_add_f32_e32 v72, v78, v72
	v_sub_f32_e32 v78, v95, v234
	v_exp_f32_e32 v78, v78
	v_exp_f32_e32 v95, v79
	v_cvt_pk_bf16_f32 v77, v77, v78
	v_add_f32_e32 v79, v95, v78
	v_add_f32_e32 v72, v79, v72
	v_sub_f32_e32 v79, v96, v234
	v_exp_f32_e32 v79, v79
	v_exp_f32_e32 v96, v80
	s_nop 0
	v_add_f32_e32 v80, v96, v79
	v_add_f32_e32 v72, v80, v72
	v_sub_f32_e32 v80, v97, v234
	v_exp_f32_e32 v97, v80
	v_sub_f32_e32 v80, v81, v234
	v_exp_f32_e32 v238, v80
	v_cvt_pk_bf16_f32 v81, v86, v87
	v_cvt_pk_bf16_f32 v78, v79, v97
	v_add_f32_e32 v80, v238, v97
	v_add_f32_e32 v72, v80, v72
	v_sub_f32_e32 v80, v98, v234
	v_exp_f32_e32 v98, v80
	v_sub_f32_e32 v80, v82, v234
	v_exp_f32_e32 v239, v80
	v_cvt_pk_bf16_f32 v82, v88, v89
	v_add_f32_e32 v80, v239, v98
	v_add_f32_e32 v72, v80, v72
	v_sub_f32_e32 v80, v99, v234
	v_exp_f32_e32 v99, v80
	v_sub_f32_e32 v80, v83, v234
	v_exp_f32_e32 v234, v80
	v_cvt_pk_bf16_f32 v83, v73, v74
	v_cvt_pk_bf16_f32 v79, v98, v99
	v_cvt_pk_bf16_f32 v73, v70, v71
	v_add_f32_e32 v80, v234, v99
	v_add_f32_e32 v84, v80, v72
	v_cvt_pk_bf16_f32 v80, v235, v85
	v_add_u32_e32 v85, s90, v196
	v_add3_u32 v85, v85, v197, v198
	v_cvt_pk_bf16_f32 v72, v68, v69
	v_cvt_pk_bf16_f32 v68, v92, v93
	ds_read_b64_tr_b16 v[86:87], v85 offset:16384
	ds_read_b64_tr_b16 v[88:89], v85 offset:16896
	ds_read_b64_tr_b16 v[90:91], v85 offset:20480
	ds_read_b64_tr_b16 v[92:93], v85 offset:20992
	s_waitcnt lgkmcnt(0)
	v_mfma_f32_32x32x16_bf16 v[52:67], v[80:83], v[86:89], v[52:67]
	v_cvt_pk_bf16_f32 v74, v236, v237
	v_cvt_pk_bf16_f32 v69, v94, v95
	v_cvt_pk_bf16_f32 v70, v96, v238
	v_cvt_pk_bf16_f32 v71, v239, v234
	v_fmac_f32_e32 v84, v232, v233
	v_mfma_f32_32x32x16_bf16 v[36:51], v[80:83], v[90:93], v[36:51]
	ds_read_b64_tr_b16 v[86:87], v85 offset:17408
	ds_read_b64_tr_b16 v[88:89], v85 offset:17920
	ds_read_b64_tr_b16 v[90:91], v85 offset:21504
	ds_read_b64_tr_b16 v[92:93], v85 offset:22016
	s_waitcnt lgkmcnt(0)
	v_mfma_f32_32x32x16_bf16 v[52:67], v[76:79], v[86:89], v[52:67]
	v_mfma_f32_32x32x16_bf16 v[36:51], v[76:79], v[90:93], v[36:51]
	ds_read_b64_tr_b16 v[86:87], v85 offset:18432
	ds_read_b64_tr_b16 v[88:89], v85 offset:18944
	ds_read_b64_tr_b16 v[90:91], v85 offset:22528
	ds_read_b64_tr_b16 v[92:93], v85 offset:23040
	s_waitcnt lgkmcnt(0)
	v_mfma_f32_32x32x16_bf16 v[52:67], v[72:75], v[86:89], v[52:67]
	v_mfma_f32_32x32x16_bf16 v[36:51], v[72:75], v[90:93], v[36:51]
	ds_read_b64_tr_b16 v[86:87], v85 offset:19456
	ds_read_b64_tr_b16 v[88:89], v85 offset:19968
	ds_read_b64_tr_b16 v[90:91], v85 offset:23552
	ds_read_b64_tr_b16 v[92:93], v85 offset:24064
	v_add_u32_e32 v85, s14, v148
	v_sub_u32_e32 v239, v85, v193
	v_mov_b32_e32 v237, 0x3f803f80
	v_mov_b32_e32 v238, 0x3f800000
	s_waitcnt lgkmcnt(0)
; #define MFMA32(a, b, c) __builtin_amdgcn_mfma_f32_32x32x16_bf16((a), (b), (c), 0, 0, 0)
; template <bool CMP> DI void tile_compute(LAS unsigned char* lds, int buf, const bf16x8 (&q)[4], int lo, int hv, ASt& st, f32x16& imp0, f32x16& imp1, int jt, LAS float* wsf, int lane) {
;     ...
;     if (CMP) {
; #pragma unroll
;         for (int s = 0; s < 4; ++s) {
;             bf16x8 w0, w1;
; #pragma unroll
;             for (int j = 0; j < 8; ++j) { const int jj = 64 * jt + 16 * s + 8 * (j >> 2) + 4 * hi + (j & 3);
;                 const int n0 = r, n1 = 32 + r;
;                 w0[j] = (jj >= 4 * n0 - 1 && jj <= 4 * n0 + 3) ? (short)0x3F80 : (short)0;
;                 w1[j] = (jj >= 4 * n1 - 1 && jj <= 4 * n1 + 3) ? (short)0x3F80 : (short)0; }
;             imp0 = MFMA32(pa[s], w0, imp0); imp1 = MFMA32(pa[s], w1, imp1); asm volatile("" ::: "memory");
;         }
;     }
	v_mfma_f32_32x32x16_bf16 v[52:67], v[68:71], v[86:89], v[52:67]
	v_mfma_f32_32x32x16_bf16 v[36:51], v[68:71], v[90:93], v[36:51]
	s_add_i32 s14, s14, 64
	v_add_u32_e32 v235, 0, v239
	v_cmp_eq_u32_e32 vcc, -4, v235
	s_nop 1
	v_cndmask_b32_e32 v87, 0, v238, vcc
	v_cmp_eq_u32_e32 vcc, 0, v235
	s_nop 1
	v_cndmask_b32_e32 v86, 0, v237, vcc
	v_cndmask_b32_e32 v87, v87, v237, vcc
	v_cmp_eq_u32_e32 vcc, -12, v235
	s_nop 1
	v_cndmask_b32_e32 v89, 0, v238, vcc
	v_cmp_eq_u32_e32 vcc, -8, v235
	s_nop 1
	v_cndmask_b32_e32 v88, 0, v237, vcc
	v_cndmask_b32_e32 v89, v89, v237, vcc
	v_add_u32_e32 v236, 0xffffff80, v239
	v_cmp_eq_u32_e32 vcc, -4, v236
	s_nop 1
	v_cndmask_b32_e32 v241, 0, v238, vcc
	v_cmp_eq_u32_e32 vcc, 0, v236
	s_nop 1
	v_cndmask_b32_e32 v240, 0, v237, vcc
	v_cndmask_b32_e32 v241, v241, v237, vcc
	v_cmp_eq_u32_e32 vcc, -12, v236
	s_nop 1
	v_cndmask_b32_e32 v243, 0, v238, vcc
	v_cmp_eq_u32_e32 vcc, -8, v236
	s_nop 1
	v_cndmask_b32_e32 v242, 0, v237, vcc
	v_cndmask_b32_e32 v243, v243, v237, vcc
	s_nop 7
	v_mfma_f32_32x32x16_bf16 v[20:35], v[80:83], v[86:89], v[20:35]
	v_mfma_f32_32x32x16_bf16 v[4:19], v[80:83], v[240:243], v[4:19]
	v_add_u32_e32 v235, 16, v239
	v_cmp_eq_u32_e32 vcc, -4, v235
	s_nop 1
	v_cndmask_b32_e32 v81, 0, v238, vcc
	v_cmp_eq_u32_e32 vcc, 0, v235
	s_nop 1
	v_cndmask_b32_e32 v80, 0, v237, vcc
	v_cndmask_b32_e32 v81, v81, v237, vcc
	v_cmp_eq_u32_e32 vcc, -12, v235
	s_nop 1
	v_cndmask_b32_e32 v83, 0, v238, vcc
	v_cmp_eq_u32_e32 vcc, -8, v235
	s_nop 1
	v_cndmask_b32_e32 v82, 0, v237, vcc
	v_cndmask_b32_e32 v83, v83, v237, vcc
	v_add_u32_e32 v236, 0xffffff90, v239
	v_cmp_eq_u32_e32 vcc, -4, v236
	s_nop 1
	v_cndmask_b32_e32 v241, 0, v238, vcc
	v_cmp_eq_u32_e32 vcc, 0, v236
	s_nop 1
	v_cndmask_b32_e32 v240, 0, v237, vcc
	v_cndmask_b32_e32 v241, v241, v237, vcc
	v_cmp_eq_u32_e32 vcc, -12, v236
	s_nop 1
	v_cndmask_b32_e32 v243, 0, v238, vcc
	v_cmp_eq_u32_e32 vcc, -8, v236
	s_nop 1
	v_cndmask_b32_e32 v242, 0, v237, vcc
	v_cndmask_b32_e32 v243, v243, v237, vcc
	s_nop 7
	v_mfma_f32_32x32x16_bf16 v[20:35], v[76:79], v[80:83], v[20:35]
	v_mfma_f32_32x32x16_bf16 v[4:19], v[76:79], v[240:243], v[4:19]
	v_add_u32_e32 v235, 32, v239
	v_cmp_eq_u32_e32 vcc, -4, v235
	s_nop 1
	v_cndmask_b32_e32 v77, 0, v238, vcc
	v_cmp_eq_u32_e32 vcc, 0, v235
	s_nop 1
	v_cndmask_b32_e32 v76, 0, v237, vcc
	v_cndmask_b32_e32 v77, v77, v237, vcc
	v_cmp_eq_u32_e32 vcc, -12, v235
	s_nop 1
	v_cndmask_b32_e32 v79, 0, v238, vcc
	v_cmp_eq_u32_e32 vcc, -8, v235
	s_nop 1
	v_cndmask_b32_e32 v78, 0, v237, vcc
	v_cndmask_b32_e32 v79, v79, v237, vcc
	v_add_u32_e32 v236, 0xffffffa0, v239
	v_cmp_eq_u32_e32 vcc, -4, v236
	s_nop 1
	v_cndmask_b32_e32 v241, 0, v238, vcc
	v_cmp_eq_u32_e32 vcc, 0, v236
	s_nop 1
	v_cndmask_b32_e32 v240, 0, v237, vcc
	v_cndmask_b32_e32 v241, v241, v237, vcc
	v_cmp_eq_u32_e32 vcc, -12, v236
	s_nop 1
	v_cndmask_b32_e32 v243, 0, v238, vcc
	v_cmp_eq_u32_e32 vcc, -8, v236
	s_nop 1
	v_cndmask_b32_e32 v242, 0, v237, vcc
	v_cndmask_b32_e32 v243, v243, v237, vcc
	s_nop 7
	v_mfma_f32_32x32x16_bf16 v[20:35], v[72:75], v[76:79], v[20:35]
	v_mfma_f32_32x32x16_bf16 v[4:19], v[72:75], v[240:243], v[4:19]
	s_add_u32 s88, s88, 0x2000
	s_addc_u32 s89, s89, 0
	v_add_u32_e32 v235, 48, v239
	v_cmp_eq_u32_e32 vcc, -4, v235
	s_nop 1
	v_cndmask_b32_e32 v73, 0, v238, vcc
	v_cmp_eq_u32_e32 vcc, 0, v235
	s_nop 1
	v_cndmask_b32_e32 v72, 0, v237, vcc
	v_cndmask_b32_e32 v73, v73, v237, vcc
	v_cmp_eq_u32_e32 vcc, -12, v235
	s_nop 1
	v_cndmask_b32_e32 v75, 0, v238, vcc
	v_cmp_eq_u32_e32 vcc, -8, v235
	s_nop 1
	v_cndmask_b32_e32 v74, 0, v237, vcc
	v_cndmask_b32_e32 v75, v75, v237, vcc
	v_add_u32_e32 v236, 0xffffffb0, v239
	v_cmp_eq_u32_e32 vcc, -4, v236
	s_nop 1
	v_cndmask_b32_e32 v241, 0, v238, vcc
	v_cmp_eq_u32_e32 vcc, 0, v236
	s_nop 1
	v_cndmask_b32_e32 v240, 0, v237, vcc
	v_cndmask_b32_e32 v241, v241, v237, vcc
	v_cmp_eq_u32_e32 vcc, -12, v236
	s_nop 1
	v_cndmask_b32_e32 v243, 0, v238, vcc
	v_cmp_eq_u32_e32 vcc, -8, v236
	s_nop 1
	v_cndmask_b32_e32 v242, 0, v237, vcc
	v_cndmask_b32_e32 v243, v243, v237, vcc
	s_nop 7
	v_mfma_f32_32x32x16_bf16 v[20:35], v[68:71], v[72:75], v[20:35]
	s_add_i32 s3, s3, 1
	s_cmp_eq_u32 s84, s14
	v_mfma_f32_32x32x16_bf16 v[4:19], v[68:71], v[240:243], v[4:19]
	s_cbranch_scc1 .LBB0_557
	v_mov_b32_e32 v232, v84
	v_mov_b32_e32 v233, v141
	s_branch .LBB0_547

; #define LAS __attribute__((address_space(3)))
; #define LDS_WAIT() asm volatile("s_waitcnt lgkmcnt(0)" ::: "memory")
; #define MFMA32(a, b, c) __builtin_amdgcn_mfma_f32_32x32x16_bf16((a), (b), (c), 0, 0, 0)
; template <bool CMP> DI void tile_compute(LAS unsigned char* lds, int buf, const bf16x8 (&q)[4], int lo, int hv, ASt& st, f32x16& imp0, f32x16& imp1, int jt, LAS float* wsf, int lane) {
;     ...
;     const float msub = (!anyPart && dead) ? 1e30f : mnew;
; #pragma unroll
;     for (int rg = 0; rg < 16; ++rg) { p0[rg] = __builtin_amdgcn_exp2f(p0[rg] - msub); p1[rg] = __builtin_amdgcn_exp2f(p1[rg] - msub); sum += p0[rg] + p1[rg]; }
;     st.l = st.l * alpha + sum;
;     if (__builtin_amdgcn_ballot_w64(alpha != 1.f) != 0ull) {
;         if (hi == 0) wsf[r] = alpha;
;         LDS_WAIT();
; #pragma unroll
;         for (int g4 = 0; g4 < 4; ++g4) { const f32x4 f = *(const LAS f32x4*)(wsf + 8 * g4 + 4 * hi);
; #pragma unroll
;             for (int k = 0; k < 4; ++k) { st.o0[4 * g4 + k] *= f[k]; st.o1[4 * g4 + k] *= f[k]; if (CMP) { imp0[4 * g4 + k] *= f[k]; imp1[4 * g4 + k] *= f[k]; } } }
;         LDS_WAIT();
;     }
;     bf16x8 pa[4];
;     pa[0] = pack8(p0[0], p0[1], p0[2], p0[3], p0[4], p0[5], p0[6], p0[7]); pa[1] = pack8(p0[8], p0[9], p0[10], p0[11], p0[12], p0[13], p0[14], p0[15]);
;     pa[2] = pack8(p1[0], p1[1], p1[2], p1[3], p1[4], p1[5], p1[6], p1[7]); pa[3] = pack8(p1[8], p1[9], p1[10], p1[11], p1[12], p1[13], p1[14], p1[15]);
;     const LAS unsigned char* vb = lds + A_VT + buf * 8192 + (4 * hi + ((lane & 15) >> 2)) * 64 + ((lane >> 4) & 1) * 32 + (lane & 3) * 8;
; #pragma unroll
;     for (int s = 0; s < 4; ++s) {
;         const bf16x8 v0 = cat8(vtr(vb + s * 1024), vtr(vb + s * 1024 + 512));
;         const bf16x8 v1 = cat8(vtr(vb + 4096 + s * 1024), vtr(vb + 4096 + s * 1024 + 512));
;         st.o0 = MFMA32(pa[s], v0, st.o0); st.o1 = MFMA32(pa[s], v1, st.o1);
;     }
;     if (CMP) {
; #pragma unroll
;         for (int s = 0; s < 4; ++s) {
;             bf16x8 w0, w1;
; #pragma unroll
;             for (int j = 0; j < 8; ++j) { const int jj = 64 * jt + 16 * s + 8 * (j >> 2) + 4 * hi + (j & 3);
;                 const int n0 = r, n1 = 32 + r;
;                 w0[j] = (jj >= 4 * n0 - 1 && jj <= 4 * n0 + 3) ? (short)0x3F80 : (short)0;
;                 w1[j] = (jj >= 4 * n1 - 1 && jj <= 4 * n1 + 3) ? (short)0x3F80 : (short)0; }
.LBB0_1168:
	v_cndmask_b32_e64 v229, v141, v218, s[80:81]
	v_sub_f32_e32 v84, v84, v229
	v_sub_f32_e32 v68, v68, v229
	v_exp_f32_e32 v230, v84
	v_exp_f32_e32 v68, v68
	v_sub_f32_e32 v85, v85, v229
	v_sub_f32_e32 v69, v69, v229
	v_exp_f32_e32 v85, v85
	v_exp_f32_e32 v69, v69
	v_sub_f32_e32 v86, v86, v229
	v_sub_f32_e32 v70, v70, v229
	v_exp_f32_e32 v86, v86
	v_exp_f32_e32 v70, v70
	v_sub_f32_e32 v87, v87, v229
	v_sub_f32_e32 v71, v71, v229
	v_exp_f32_e32 v87, v87
	v_exp_f32_e32 v71, v71
	v_add_f32_e32 v84, v68, v230
	v_add_f32_e32 v84, 0, v84
	v_add_f32_e32 v231, v69, v85
	v_add_f32_e32 v84, v231, v84
	v_add_f32_e32 v231, v70, v86
	v_add_f32_e32 v84, v231, v84
	v_add_f32_e32 v231, v71, v87
	v_sub_f32_e32 v88, v88, v229
	v_sub_f32_e32 v72, v72, v229
	v_add_f32_e32 v84, v231, v84
	v_exp_f32_e32 v88, v88
	v_exp_f32_e32 v231, v72
	v_sub_f32_e32 v73, v73, v229
	v_exp_f32_e32 v232, v73
	v_sub_f32_e32 v74, v74, v229
	v_add_f32_e32 v72, v231, v88
	v_add_f32_e32 v72, v72, v84
	v_sub_f32_e32 v84, v89, v229
	v_exp_f32_e32 v89, v84
	v_sub_f32_e32 v75, v75, v229
	v_exp_f32_e32 v75, v75
	v_sub_f32_e32 v76, v76, v229
	v_add_f32_e32 v73, v232, v89
	v_add_f32_e32 v72, v73, v72
	v_sub_f32_e32 v73, v90, v229
	v_exp_f32_e32 v73, v73
	v_exp_f32_e32 v90, v74
	v_sub_f32_e32 v77, v77, v229
	v_sub_f32_e32 v78, v78, v229
	v_sub_f32_e32 v79, v79, v229
	v_add_f32_e32 v74, v90, v73
	v_add_f32_e32 v72, v74, v72
	v_sub_f32_e32 v74, v91, v229
	v_exp_f32_e32 v74, v74
	v_sub_f32_e32 v80, v80, v229
	v_subrev_u32_e32 v226, 64, v226
	v_add_f32_e32 v84, v75, v74
	v_add_f32_e32 v72, v84, v72
	v_sub_f32_e32 v84, v92, v229
	v_exp_f32_e32 v91, v84
	v_exp_f32_e32 v92, v76
	v_cvt_pk_bf16_f32 v75, v90, v75
	v_add_f32_e32 v76, v92, v91
	v_add_f32_e32 v72, v76, v72
	v_sub_f32_e32 v76, v93, v229
	v_exp_f32_e32 v76, v76
	v_exp_f32_e32 v93, v77
	s_nop 0
	v_add_f32_e32 v77, v93, v76
	v_add_f32_e32 v72, v77, v72
	v_sub_f32_e32 v77, v94, v229
	v_exp_f32_e32 v77, v77
	v_exp_f32_e32 v94, v78
	v_cvt_pk_bf16_f32 v76, v91, v76
	v_add_f32_e32 v78, v94, v77
	v_add_f32_e32 v72, v78, v72
	v_sub_f32_e32 v78, v95, v229
	v_exp_f32_e32 v78, v78
	v_exp_f32_e32 v95, v79
	v_cvt_pk_bf16_f32 v77, v77, v78
	v_add_f32_e32 v79, v95, v78
	v_add_f32_e32 v72, v79, v72
	v_sub_f32_e32 v79, v96, v229
	v_exp_f32_e32 v79, v79
	v_exp_f32_e32 v96, v80
	s_nop 0
	v_add_f32_e32 v80, v96, v79
	v_add_f32_e32 v72, v80, v72
	v_sub_f32_e32 v80, v97, v229
	v_exp_f32_e32 v97, v80
	v_sub_f32_e32 v80, v81, v229
	v_exp_f32_e32 v233, v80
	v_cvt_pk_bf16_f32 v81, v86, v87
	v_cvt_pk_bf16_f32 v78, v79, v97
	v_add_f32_e32 v80, v233, v97
	v_add_f32_e32 v72, v80, v72
	v_sub_f32_e32 v80, v98, v229
	v_exp_f32_e32 v98, v80
	v_sub_f32_e32 v80, v82, v229
	v_exp_f32_e32 v234, v80
	v_cvt_pk_bf16_f32 v82, v88, v89
	v_add_f32_e32 v80, v234, v98
	v_add_f32_e32 v72, v80, v72
	v_sub_f32_e32 v80, v99, v229
	v_exp_f32_e32 v99, v80
	v_sub_f32_e32 v80, v83, v229
	v_exp_f32_e32 v229, v80
	v_cvt_pk_bf16_f32 v83, v73, v74
	v_cvt_pk_bf16_f32 v79, v98, v99
	v_cvt_pk_bf16_f32 v73, v70, v71
	v_add_f32_e32 v80, v229, v99
	v_add_f32_e32 v84, v80, v72
	v_cvt_pk_bf16_f32 v80, v230, v85
	v_add_u32_e32 v85, s28, v188
	v_add3_u32 v85, v85, v187, v186
	v_cvt_pk_bf16_f32 v72, v68, v69
	v_cvt_pk_bf16_f32 v68, v92, v93
	ds_read_b64_tr_b16 v[86:87], v85 offset:16384
	ds_read_b64_tr_b16 v[88:89], v85 offset:16896
	ds_read_b64_tr_b16 v[90:91], v85 offset:20480
	ds_read_b64_tr_b16 v[92:93], v85 offset:20992
	s_waitcnt lgkmcnt(0)
	v_mfma_f32_32x32x16_bf16 v[52:67], v[80:83], v[86:89], v[52:67]
	v_cvt_pk_bf16_f32 v74, v231, v232
	v_cvt_pk_bf16_f32 v69, v94, v95
	v_cvt_pk_bf16_f32 v70, v96, v233
	v_cvt_pk_bf16_f32 v71, v234, v229
	v_fmac_f32_e32 v84, v227, v228
	v_mfma_f32_32x32x16_bf16 v[36:51], v[80:83], v[90:93], v[36:51]
	ds_read_b64_tr_b16 v[86:87], v85 offset:17408
	ds_read_b64_tr_b16 v[88:89], v85 offset:17920
	ds_read_b64_tr_b16 v[90:91], v85 offset:21504
	ds_read_b64_tr_b16 v[92:93], v85 offset:22016
	s_waitcnt lgkmcnt(0)
	v_mfma_f32_32x32x16_bf16 v[52:67], v[76:79], v[86:89], v[52:67]
	v_mfma_f32_32x32x16_bf16 v[36:51], v[76:79], v[90:93], v[36:51]
	ds_read_b64_tr_b16 v[86:87], v85 offset:18432
	ds_read_b64_tr_b16 v[88:89], v85 offset:18944
	ds_read_b64_tr_b16 v[90:91], v85 offset:22528
	ds_read_b64_tr_b16 v[92:93], v85 offset:23040
	s_waitcnt lgkmcnt(0)
	v_mfma_f32_32x32x16_bf16 v[52:67], v[72:75], v[86:89], v[52:67]
	v_mfma_f32_32x32x16_bf16 v[36:51], v[72:75], v[90:93], v[36:51]
	ds_read_b64_tr_b16 v[86:87], v85 offset:19456
	ds_read_b64_tr_b16 v[88:89], v85 offset:19968
	ds_read_b64_tr_b16 v[90:91], v85 offset:23552
	ds_read_b64_tr_b16 v[92:93], v85 offset:24064
	v_add_u32_e32 v85, s16, v148
	v_sub_u32_e32 v239, v85, v196
	v_mov_b32_e32 v237, 0x3f803f80
	v_mov_b32_e32 v238, 0x3f800000
	s_waitcnt lgkmcnt(0)
; #define MFMA32(a, b, c) __builtin_amdgcn_mfma_f32_32x32x16_bf16((a), (b), (c), 0, 0, 0)
; template <bool CMP> DI void tile_compute(LAS unsigned char* lds, int buf, const bf16x8 (&q)[4], int lo, int hv, ASt& st, f32x16& imp0, f32x16& imp1, int jt, LAS float* wsf, int lane) {
;     ...
;     if (CMP) {
; #pragma unroll
;         for (int s = 0; s < 4; ++s) {
;             bf16x8 w0, w1;
; #pragma unroll
;             for (int j = 0; j < 8; ++j) { const int jj = 64 * jt + 16 * s + 8 * (j >> 2) + 4 * hi + (j & 3);
;                 const int n0 = r, n1 = 32 + r;
;                 w0[j] = (jj >= 4 * n0 - 1 && jj <= 4 * n0 + 3) ? (short)0x3F80 : (short)0;
;                 w1[j] = (jj >= 4 * n1 - 1 && jj <= 4 * n1 + 3) ? (short)0x3F80 : (short)0; }
;             imp0 = MFMA32(pa[s], w0, imp0); imp1 = MFMA32(pa[s], w1, imp1); asm volatile("" ::: "memory");
;         }
;     }
	v_mfma_f32_32x32x16_bf16 v[52:67], v[68:71], v[86:89], v[52:67]
	v_mfma_f32_32x32x16_bf16 v[36:51], v[68:71], v[90:93], v[36:51]
	s_add_i32 s16, s16, 64
	v_add_u32_e32 v235, 0, v239
	v_cmp_eq_u32_e32 vcc, -4, v235
	s_nop 1
	v_cndmask_b32_e32 v87, 0, v238, vcc
	v_cmp_eq_u32_e32 vcc, 0, v235
	s_nop 1
	v_cndmask_b32_e32 v86, 0, v237, vcc
	v_cndmask_b32_e32 v87, v87, v237, vcc
	v_cmp_eq_u32_e32 vcc, -12, v235
	s_nop 1
	v_cndmask_b32_e32 v89, 0, v238, vcc
	v_cmp_eq_u32_e32 vcc, -8, v235
	s_nop 1
	v_cndmask_b32_e32 v88, 0, v237, vcc
	v_cndmask_b32_e32 v89, v89, v237, vcc
	v_add_u32_e32 v236, 0xffffff80, v239
	v_cmp_eq_u32_e32 vcc, -4, v236
	s_nop 1
	v_cndmask_b32_e32 v241, 0, v238, vcc
	v_cmp_eq_u32_e32 vcc, 0, v236
	s_nop 1
	v_cndmask_b32_e32 v240, 0, v237, vcc
	v_cndmask_b32_e32 v241, v241, v237, vcc
	v_cmp_eq_u32_e32 vcc, -12, v236
	s_nop 1
	v_cndmask_b32_e32 v243, 0, v238, vcc
	v_cmp_eq_u32_e32 vcc, -8, v236
	s_nop 1
	v_cndmask_b32_e32 v242, 0, v237, vcc
	v_cndmask_b32_e32 v243, v243, v237, vcc
	s_nop 7
	v_mfma_f32_32x32x16_bf16 v[20:35], v[80:83], v[86:89], v[20:35]
	v_mfma_f32_32x32x16_bf16 v[4:19], v[80:83], v[240:243], v[4:19]
	v_add_u32_e32 v235, 16, v239
	v_cmp_eq_u32_e32 vcc, -4, v235
	s_nop 1
	v_cndmask_b32_e32 v81, 0, v238, vcc
	v_cmp_eq_u32_e32 vcc, 0, v235
	s_nop 1
	v_cndmask_b32_e32 v80, 0, v237, vcc
	v_cndmask_b32_e32 v81, v81, v237, vcc
	v_cmp_eq_u32_e32 vcc, -12, v235
	s_nop 1
	v_cndmask_b32_e32 v83, 0, v238, vcc
	v_cmp_eq_u32_e32 vcc, -8, v235
	s_nop 1
	v_cndmask_b32_e32 v82, 0, v237, vcc
	v_cndmask_b32_e32 v83, v83, v237, vcc
	v_add_u32_e32 v236, 0xffffff90, v239
	v_cmp_eq_u32_e32 vcc, -4, v236
	s_nop 1
	v_cndmask_b32_e32 v241, 0, v238, vcc
	v_cmp_eq_u32_e32 vcc, 0, v236
	s_nop 1
	v_cndmask_b32_e32 v240, 0, v237, vcc
	v_cndmask_b32_e32 v241, v241, v237, vcc
	v_cmp_eq_u32_e32 vcc, -12, v236
	s_nop 1
	v_cndmask_b32_e32 v243, 0, v238, vcc
	v_cmp_eq_u32_e32 vcc, -8, v236
	s_nop 1
	v_cndmask_b32_e32 v242, 0, v237, vcc
	v_cndmask_b32_e32 v243, v243, v237, vcc
	s_nop 7
	v_mfma_f32_32x32x16_bf16 v[20:35], v[76:79], v[80:83], v[20:35]
	v_mfma_f32_32x32x16_bf16 v[4:19], v[76:79], v[240:243], v[4:19]
	v_add_u32_e32 v235, 32, v239
	v_cmp_eq_u32_e32 vcc, -4, v235
	s_nop 1
	v_cndmask_b32_e32 v77, 0, v238, vcc
	v_cmp_eq_u32_e32 vcc, 0, v235
	s_nop 1
	v_cndmask_b32_e32 v76, 0, v237, vcc
	v_cndmask_b32_e32 v77, v77, v237, vcc
	v_cmp_eq_u32_e32 vcc, -12, v235
	s_nop 1
	v_cndmask_b32_e32 v79, 0, v238, vcc
	v_cmp_eq_u32_e32 vcc, -8, v235
	s_nop 1
	v_cndmask_b32_e32 v78, 0, v237, vcc
	v_cndmask_b32_e32 v79, v79, v237, vcc
	v_add_u32_e32 v236, 0xffffffa0, v239
	v_cmp_eq_u32_e32 vcc, -4, v236
	s_nop 1
	v_cndmask_b32_e32 v241, 0, v238, vcc
	v_cmp_eq_u32_e32 vcc, 0, v236
	s_nop 1
	v_cndmask_b32_e32 v240, 0, v237, vcc
	v_cndmask_b32_e32 v241, v241, v237, vcc
	v_cmp_eq_u32_e32 vcc, -12, v236
	s_nop 1
	v_cndmask_b32_e32 v243, 0, v238, vcc
	v_cmp_eq_u32_e32 vcc, -8, v236
	s_nop 1
	v_cndmask_b32_e32 v242, 0, v237, vcc
	v_cndmask_b32_e32 v243, v243, v237, vcc
	s_nop 7
	v_mfma_f32_32x32x16_bf16 v[20:35], v[72:75], v[76:79], v[20:35]
	v_mfma_f32_32x32x16_bf16 v[4:19], v[72:75], v[240:243], v[4:19]
	s_add_u32 s88, s88, 0x2000
	s_addc_u32 s89, s89, 0
	v_add_u32_e32 v235, 48, v239
	v_cmp_eq_u32_e32 vcc, -4, v235
	s_nop 1
	v_cndmask_b32_e32 v73, 0, v238, vcc
	v_cmp_eq_u32_e32 vcc, 0, v235
	s_nop 1
	v_cndmask_b32_e32 v72, 0, v237, vcc
	v_cndmask_b32_e32 v73, v73, v237, vcc
	v_cmp_eq_u32_e32 vcc, -12, v235
	s_nop 1
	v_cndmask_b32_e32 v75, 0, v238, vcc
	v_cmp_eq_u32_e32 vcc, -8, v235
	s_nop 1
	v_cndmask_b32_e32 v74, 0, v237, vcc
	v_cndmask_b32_e32 v75, v75, v237, vcc
	v_add_u32_e32 v236, 0xffffffb0, v239
	v_cmp_eq_u32_e32 vcc, -4, v236
	s_nop 1
	v_cndmask_b32_e32 v241, 0, v238, vcc
	v_cmp_eq_u32_e32 vcc, 0, v236
	s_nop 1
	v_cndmask_b32_e32 v240, 0, v237, vcc
	v_cndmask_b32_e32 v241, v241, v237, vcc
	v_cmp_eq_u32_e32 vcc, -12, v236
	s_nop 1
	v_cndmask_b32_e32 v243, 0, v238, vcc
	v_cmp_eq_u32_e32 vcc, -8, v236
	s_nop 1
	v_cndmask_b32_e32 v242, 0, v237, vcc
	v_cndmask_b32_e32 v243, v243, v237, vcc
	s_nop 7
	v_mfma_f32_32x32x16_bf16 v[20:35], v[68:71], v[72:75], v[20:35]
	s_add_i32 s6, s6, 1
	s_cmp_eq_u32 s90, s16
	v_mfma_f32_32x32x16_bf16 v[4:19], v[68:71], v[240:243], v[4:19]
	s_cbranch_scc1 .LBB0_1170
	v_mov_b32_e32 v227, v84
	v_mov_b32_e32 v228, v141
	s_branch .LBB0_1160
